# v059 + one static s_setprio 1 for waves 4-7 across the static-stabiliser attention loop (restored to 0 at loop exit)
# speedup vs baseline: 1.0032x; 1.0032x over previous
.LBB0_496:
	v_ashrrev_i32_e32 v191, 31, v190
	v_lshlrev_b32_e32 v207, 2, v168
	s_waitcnt lgkmcnt(7)
	v_mfma_f32_32x32x16_bf16 v[66:81], v[162:165], v[130:133], v[34:49]
	v_exp_f32_e32 v65, v98
	v_exp_f32_e32 v162, v99
	s_nop 0
	v_cvt_pk_bf16_f32 v98, v65, v162
	v_add_f32_e32 v65, 0, v65
	v_add_f32_e32 v65, v162, v65
	s_waitcnt lgkmcnt(5)
	v_mfma_f32_32x32x16_bf16 v[34:49], v[158:161], v[130:133], v[34:49]
	v_exp_f32_e32 v158, v100
	v_exp_f32_e32 v159, v101
	v_add_f32_e32 v65, v158, v65
	v_cvt_pk_bf16_f32 v99, v158, v159
	v_add_f32_e32 v65, v159, v65
	v_mfma_f32_32x32x16_bf16 v[66:81], v[154:157], v[134:137], v[66:81]
	v_exp_f32_e32 v154, v102
	v_exp_f32_e32 v155, v103
	v_add_f32_e32 v65, v154, v65
	v_cvt_pk_bf16_f32 v100, v154, v155
	v_add_f32_e32 v65, v155, v65
	s_waitcnt lgkmcnt(3)
	v_mfma_f32_32x32x16_bf16 v[66:81], v[126:129], v[138:141], v[66:81]
	v_exp_f32_e32 v104, v104
	v_exp_f32_e32 v105, v105
	v_add_f32_e32 v65, v104, v65
	v_cvt_pk_bf16_f32 v101, v104, v105
	v_add_f32_e32 v65, v105, v65
	s_waitcnt lgkmcnt(2)
	v_mfma_f32_32x32x16_bf16 v[66:81], v[122:125], v[142:145], v[66:81]
	v_exp_f32_e32 v106, v106
	v_exp_f32_e32 v107, v107
	s_nop 0
	v_cvt_pk_bf16_f32 v102, v106, v107
	v_exp_f32_e32 v108, v108
	v_mfma_f32_32x32x16_bf16 v[34:49], v[60:63], v[134:137], v[34:49]
	v_exp_f32_e32 v109, v109
	v_add_f32_e32 v60, v106, v65
	v_add_f32_e32 v60, v107, v60
	v_add_f32_e32 v60, v108, v60
	v_cvt_pk_bf16_f32 v103, v108, v109
	v_exp_f32_e32 v110, v110
	v_exp_f32_e32 v111, v111
	s_waitcnt lgkmcnt(1)
	v_mfma_f32_32x32x16_bf16 v[34:49], v[56:59], v[138:141], v[34:49]
	v_add_f32_e32 v60, v109, v60
	v_add_f32_e32 v60, v110, v60
	v_cvt_pk_bf16_f32 v104, v110, v111
	v_exp_f32_e32 v112, v112
	v_exp_f32_e32 v162, v113
	v_add_f32_e32 v60, v111, v60
	v_add_f32_e32 v65, v112, v60
	v_cvt_pk_bf16_f32 v105, v112, v162
	s_setprio 0
	ds_read_b128 v[56:59], v64 offset:27648
	ds_read_b128 v[60:63], v64 offset:27680
	ds_read_b128 v[106:109], v64 offset:27712
	ds_read_b128 v[110:113], v64 offset:27744
	ds_read_b128 v[122:125], v64 offset:32256
	ds_read_b128 v[126:129], v64 offset:32288
	ds_read_b128 v[154:157], v64 offset:32320
	ds_read_b128 v[158:161], v64 offset:32352
	v_add_f32_e32 v64, v162, v65
	v_exp_f32_e32 v65, v82
	v_exp_f32_e32 v82, v83
	v_exp_f32_e32 v83, v84
	v_exp_f32_e32 v84, v85
	v_add_f32_e32 v64, v65, v64
	v_exp_f32_e32 v85, v86
	v_add_f32_e32 v64, v82, v64
	v_exp_f32_e32 v86, v87
	v_add_f32_e32 v64, v83, v64
	v_exp_f32_e32 v87, v88
	v_add_f32_e32 v64, v84, v64
	v_exp_f32_e32 v88, v89
	v_add_f32_e32 v64, v85, v64
	v_exp_f32_e32 v89, v90
	v_add_f32_e32 v64, v86, v64
	v_exp_f32_e32 v90, v91
	v_add_f32_e32 v64, v87, v64
	v_exp_f32_e32 v91, v92
	v_add_f32_e32 v64, v88, v64
	v_exp_f32_e32 v92, v93
	v_add_f32_e32 v64, v89, v64
	v_exp_f32_e32 v93, v94
	v_add_f32_e32 v64, v90, v64
	v_exp_f32_e32 v94, v95
	v_add_f32_e32 v64, v91, v64
	v_exp_f32_e32 v95, v96
	v_add_f32_e32 v64, v92, v64
	v_exp_f32_e32 v96, v97
	v_add_f32_e32 v64, v93, v64
	v_add_f32_e32 v64, v94, v64
	v_add_f32_e32 v64, v95, v64
	v_add_f32_e32 v64, v96, v64
	v_cvt_pk_bf16_f32 v82, v65, v82
	v_cvt_pk_bf16_f32 v83, v83, v84
	v_cvt_pk_bf16_f32 v84, v85, v86
	v_cvt_pk_bf16_f32 v85, v87, v88
	v_cvt_pk_bf16_f32 v86, v89, v90
	v_cvt_pk_bf16_f32 v87, v91, v92
	v_cvt_pk_bf16_f32 v88, v93, v94
	v_cvt_pk_bf16_f32 v89, v95, v96
	s_setprio 1
	s_waitcnt lgkmcnt(7)
	v_mfma_f32_32x32x16_bf16 v[18:33], v[56:59], v[98:101], v[18:33]
	v_add_f32_e32 v210, v50, v64
	s_waitcnt lgkmcnt(3)
	v_mfma_f32_32x32x16_bf16 v[2:17], v[122:125], v[98:101], v[2:17]
	v_mfma_f32_32x32x16_bf16 v[18:33], v[60:63], v[102:105], v[18:33]
	s_waitcnt lgkmcnt(2)
	v_mfma_f32_32x32x16_bf16 v[2:17], v[126:129], v[102:105], v[2:17]
	v_mfma_f32_32x32x16_bf16 v[18:33], v[106:109], v[82:85], v[18:33]
	s_waitcnt lgkmcnt(1)
	v_mfma_f32_32x32x16_bf16 v[2:17], v[154:157], v[82:85], v[2:17]
	v_mfma_f32_32x32x16_bf16 v[18:33], v[110:113], v[86:89], v[18:33]
	s_waitcnt lgkmcnt(0)
	v_mfma_f32_32x32x16_bf16 v[2:17], v[158:161], v[86:89], v[2:17]
	v_mfma_f32_32x32x16_bf16 v[34:49], v[52:55], v[142:145], v[34:49]
	s_setprio 0
	s_movk_i32 s2, 0x4800
	s_mov_b32 s3, 0
	s_mov_b32 s0, 0x9000
	s_mov_b32 s10, 6
	v_mov_b32_e32 v50, v51
	v_mov_b32_e32 v52, v51
	v_mov_b32_e32 v53, v51
	v_mov_b32_e32 v54, v51
	v_mov_b32_e32 v55, v51
	v_mov_b32_e32 v56, v51
	v_mov_b32_e32 v57, v51
	v_mov_b32_e32 v58, v51
	v_mov_b32_e32 v59, v51
	v_mov_b32_e32 v60, v51
	v_mov_b32_e32 v61, v51
	v_mov_b32_e32 v62, v51
	v_mov_b32_e32 v63, v51
	v_mov_b32_e32 v64, v51
	v_mov_b32_e32 v65, v51
	s_waitcnt vmcnt(3)
	ds_write_b128 v169, v[114:117]
	s_waitcnt vmcnt(2)
	ds_write_b128 v170, v[118:121] offset:9216
	v_readlane_b32 s1, v255, 20
	s_nop 3
	s_cmp_lt_u32 s1, 0x42400000
	s_cbranch_scc0 .Lattn_online_pre
	v_sub_f32_e32 v50, s1, v206
	v_exp_f32_e64 v52, -v50
	v_mov_b32_e32 v206, s1
	v_readfirstlane_b32 s3, v194
	v_readfirstlane_b32 s12, v195
	v_readfirstlane_b32 s15, v208
	v_readfirstlane_b32 s23, v209
	v_add_u32_e32 v248, 0x2400, v0
	v_pk_add_f32 v[66:67], v[66:67], v[50:51] op_sel_hi:[1,0] neg_lo:[0,1] neg_hi:[0,1]
	v_pk_add_f32 v[68:69], v[68:69], v[50:51] op_sel_hi:[1,0] neg_lo:[0,1] neg_hi:[0,1]
	v_pk_add_f32 v[70:71], v[70:71], v[50:51] op_sel_hi:[1,0] neg_lo:[0,1] neg_hi:[0,1]
	v_pk_add_f32 v[72:73], v[72:73], v[50:51] op_sel_hi:[1,0] neg_lo:[0,1] neg_hi:[0,1]
	v_pk_add_f32 v[74:75], v[74:75], v[50:51] op_sel_hi:[1,0] neg_lo:[0,1] neg_hi:[0,1]
	v_pk_add_f32 v[76:77], v[76:77], v[50:51] op_sel_hi:[1,0] neg_lo:[0,1] neg_hi:[0,1]
	v_pk_add_f32 v[78:79], v[78:79], v[50:51] op_sel_hi:[1,0] neg_lo:[0,1] neg_hi:[0,1]
	v_pk_add_f32 v[80:81], v[80:81], v[50:51] op_sel_hi:[1,0] neg_lo:[0,1] neg_hi:[0,1]
	v_pk_add_f32 v[34:35], v[34:35], v[50:51] op_sel_hi:[1,0] neg_lo:[0,1] neg_hi:[0,1]
	v_pk_add_f32 v[36:37], v[36:37], v[50:51] op_sel_hi:[1,0] neg_lo:[0,1] neg_hi:[0,1]
	v_pk_add_f32 v[38:39], v[38:39], v[50:51] op_sel_hi:[1,0] neg_lo:[0,1] neg_hi:[0,1]
	v_pk_add_f32 v[40:41], v[40:41], v[50:51] op_sel_hi:[1,0] neg_lo:[0,1] neg_hi:[0,1]
	v_pk_add_f32 v[42:43], v[42:43], v[50:51] op_sel_hi:[1,0] neg_lo:[0,1] neg_hi:[0,1]
	v_pk_add_f32 v[44:45], v[44:45], v[50:51] op_sel_hi:[1,0] neg_lo:[0,1] neg_hi:[0,1]
	v_pk_add_f32 v[46:47], v[46:47], v[50:51] op_sel_hi:[1,0] neg_lo:[0,1] neg_hi:[0,1]
	v_pk_add_f32 v[48:49], v[48:49], v[50:51] op_sel_hi:[1,0] neg_lo:[0,1] neg_hi:[0,1]
	v_subrev_u32_e32 v252, s3, v194
	v_subrev_u32_e32 v253, s15, v208
	v_pk_mul_f32 v[2:3], v[2:3], v[52:53] op_sel_hi:[1,0]
	v_pk_mul_f32 v[4:5], v[4:5], v[52:53] op_sel_hi:[1,0]
	v_pk_mul_f32 v[6:7], v[6:7], v[52:53] op_sel_hi:[1,0]
	v_pk_mul_f32 v[8:9], v[8:9], v[52:53] op_sel_hi:[1,0]
	v_pk_mul_f32 v[10:11], v[10:11], v[52:53] op_sel_hi:[1,0]
	v_pk_mul_f32 v[12:13], v[12:13], v[52:53] op_sel_hi:[1,0]
	v_pk_mul_f32 v[14:15], v[14:15], v[52:53] op_sel_hi:[1,0]
	v_pk_mul_f32 v[16:17], v[16:17], v[52:53] op_sel_hi:[1,0]
	v_pk_mul_f32 v[18:19], v[18:19], v[52:53] op_sel_hi:[1,0]
	v_pk_mul_f32 v[20:21], v[20:21], v[52:53] op_sel_hi:[1,0]
	v_pk_mul_f32 v[22:23], v[22:23], v[52:53] op_sel_hi:[1,0]
	v_pk_mul_f32 v[24:25], v[24:25], v[52:53] op_sel_hi:[1,0]
	v_pk_mul_f32 v[26:27], v[26:27], v[52:53] op_sel_hi:[1,0]
	v_pk_mul_f32 v[28:29], v[28:29], v[52:53] op_sel_hi:[1,0]
	v_pk_mul_f32 v[30:31], v[30:31], v[52:53] op_sel_hi:[1,0]
	v_pk_mul_f32 v[32:33], v[32:33], v[52:53] op_sel_hi:[1,0]
	v_mul_f32_e32 v210, v210, v52
	v_xor_b32_e32 v50, 0x80000000, v206
	v_mov_b32_e32 v51, v50
	v_mov_b32_e32 v52, v50
	v_mov_b32_e32 v53, v50
	v_mov_b32_e32 v54, v50
	v_mov_b32_e32 v55, v50
	v_mov_b32_e32 v56, v50
	v_mov_b32_e32 v57, v50
	v_mov_b32_e32 v58, v50
	v_mov_b32_e32 v59, v50
	v_mov_b32_e32 v60, v50
	v_mov_b32_e32 v61, v50
	v_mov_b32_e32 v62, v50
	v_mov_b32_e32 v63, v50
	v_mov_b32_e32 v64, v50
	v_mov_b32_e32 v65, v50
	v_readfirstlane_b32 s24, v240
	s_nop 3
	s_cmp_ge_u32 s24, 0x100
	s_cbranch_scc0 .Lattn_fx_noprio
	s_setprio 1
.Lattn_fx_noprio:
.Lattn_fx_top:
	s_add_i32 s11, s10, -1
	s_min_i32 s1, s11, s58
	s_mul_i32 s44, s1, 0xa0000
	s_add_u32 s44, s3, s44
	s_addc_u32 s45, s12, 0
	s_lshl_b32 s46, s1, 7
	s_add_u32 s46, s15, s46
	s_addc_u32 s47, s23, 0
	s_add_i32 s24, s10, -2
	s_cmp_lt_u32 s24, s16
	s_cselect_b64 s[0:1], -1, 0
	s_waitcnt lgkmcnt(0)
	s_barrier
	ds_read_b128 v[162:165], v193
	ds_read_b128 v[178:181], v193 offset:4608
	ds_read_b128 v[166:169], v193 offset:32
	ds_read_b128 v[182:185], v193 offset:4640
	ds_read_b128 v[170:173], v193 offset:64
	ds_read_b128 v[186:189], v193 offset:4672
	ds_read_b128 v[174:177], v193 offset:96
	ds_read_b128 v[82:85], v193 offset:4704
	global_load_dwordx4 v[154:157], v252, s[44:45] offset:1024
	global_load_dwordx4 v[158:161], v253, s[46:47]
	v_exp_f32_e32 v66, v66
	v_exp_f32_e32 v67, v67
	v_exp_f32_e32 v68, v68
	v_exp_f32_e32 v69, v69
	v_add_f32_e32 v246, v66, v67
	v_cvt_pk_bf16_f32 v66, v66, v67
	s_waitcnt lgkmcnt(7)
	v_mfma_f32_32x32x16_bf16 v[114:129], v[162:165], v[130:133], v[50:65]
	ds_read_b128 v[86:89], v248 offset:36864
	ds_read_b128 v[216:219], v248 offset:41472
	v_exp_f32_e32 v70, v70
	v_exp_f32_e32 v71, v71
	v_add_f32_e32 v246, v68, v246
	v_add_f32_e32 v246, v69, v246
	v_cvt_pk_bf16_f32 v67, v68, v69
	s_waitcnt lgkmcnt(8)
	v_mfma_f32_32x32x16_bf16 v[98:113], v[178:181], v[130:133], v[50:65]
	ds_read_b128 v[90:93], v248 offset:36896
	ds_read_b128 v[220:223], v248 offset:41504
	v_exp_f32_e32 v72, v72
	v_exp_f32_e32 v73, v73
	v_add_f32_e32 v246, v70, v246
	v_add_f32_e32 v246, v71, v246
	v_cvt_pk_bf16_f32 v68, v70, v71
	s_waitcnt lgkmcnt(9)
	v_mfma_f32_32x32x16_bf16 v[114:129], v[166:169], v[134:137], v[114:129]
	ds_read_b128 v[94:97], v248 offset:36928
	ds_read_b128 v[224:227], v248 offset:41536
	v_exp_f32_e32 v74, v74
	v_exp_f32_e32 v75, v75
	v_add_f32_e32 v246, v72, v246
	v_add_f32_e32 v246, v73, v246
	v_cvt_pk_bf16_f32 v69, v72, v73
	s_waitcnt lgkmcnt(10)
	v_mfma_f32_32x32x16_bf16 v[98:113], v[182:185], v[134:137], v[98:113]
	ds_read_b128 v[212:215], v248 offset:36960
	ds_read_b128 v[242:245], v248 offset:41568
	v_exp_f32_e32 v76, v76
	v_exp_f32_e32 v77, v77
	v_add_f32_e32 v246, v74, v246
	v_add_f32_e32 v246, v75, v246
	v_cvt_pk_bf16_f32 v70, v74, v75
	s_waitcnt lgkmcnt(11)
	v_mfma_f32_32x32x16_bf16 v[114:129], v[170:173], v[138:141], v[114:129]
	v_exp_f32_e32 v78, v78
	v_exp_f32_e32 v79, v79
	v_add_f32_e32 v246, v76, v246
	v_add_f32_e32 v246, v77, v246
	v_cvt_pk_bf16_f32 v71, v76, v77
	s_waitcnt lgkmcnt(10)
	v_mfma_f32_32x32x16_bf16 v[98:113], v[186:189], v[138:141], v[98:113]
	v_exp_f32_e32 v80, v80
	v_exp_f32_e32 v81, v81
	v_add_f32_e32 v246, v78, v246
	v_add_f32_e32 v246, v79, v246
	v_cvt_pk_bf16_f32 v72, v78, v79
	s_waitcnt lgkmcnt(9)
	v_mfma_f32_32x32x16_bf16 v[114:129], v[174:177], v[142:145], v[114:129]
	v_exp_f32_e32 v34, v34
	v_exp_f32_e32 v35, v35
	v_add_f32_e32 v246, v80, v246
	v_add_f32_e32 v246, v81, v246
	v_cvt_pk_bf16_f32 v73, v80, v81
	s_waitcnt lgkmcnt(8)
	v_mfma_f32_32x32x16_bf16 v[98:113], v[82:85], v[142:145], v[98:113]
	v_exp_f32_e32 v36, v36
	v_exp_f32_e32 v37, v37
	v_add_f32_e32 v247, v34, v35
	v_cvt_pk_bf16_f32 v74, v34, v35
	s_waitcnt lgkmcnt(7)
	v_mfma_f32_32x32x16_bf16 v[18:33], v[86:89], v[66:69], v[18:33]
	v_exp_f32_e32 v38, v38
	v_exp_f32_e32 v39, v39
	v_add_f32_e32 v247, v36, v247
	v_add_f32_e32 v247, v37, v247
	v_cvt_pk_bf16_f32 v75, v36, v37
	s_waitcnt lgkmcnt(6)
	v_mfma_f32_32x32x16_bf16 v[2:17], v[216:219], v[66:69], v[2:17]
	v_exp_f32_e32 v40, v40
	v_exp_f32_e32 v41, v41
	v_add_f32_e32 v247, v38, v247
	v_add_f32_e32 v247, v39, v247
	v_cvt_pk_bf16_f32 v76, v38, v39
	s_waitcnt lgkmcnt(5)
	v_mfma_f32_32x32x16_bf16 v[18:33], v[90:93], v[70:73], v[18:33]
	v_exp_f32_e32 v42, v42
	v_exp_f32_e32 v43, v43
	v_add_f32_e32 v247, v40, v247
	v_add_f32_e32 v247, v41, v247
	v_cvt_pk_bf16_f32 v77, v40, v41
	s_waitcnt lgkmcnt(4)
	v_mfma_f32_32x32x16_bf16 v[2:17], v[220:223], v[70:73], v[2:17]
	v_exp_f32_e32 v44, v44
	v_exp_f32_e32 v45, v45
	v_add_f32_e32 v247, v42, v247
	v_add_f32_e32 v247, v43, v247
	v_cvt_pk_bf16_f32 v78, v42, v43
	s_waitcnt lgkmcnt(3)
	v_mfma_f32_32x32x16_bf16 v[18:33], v[94:97], v[74:77], v[18:33]
	v_exp_f32_e32 v46, v46
	v_exp_f32_e32 v47, v47
	v_add_f32_e32 v247, v44, v247
	v_add_f32_e32 v247, v45, v247
	v_cvt_pk_bf16_f32 v79, v44, v45
	s_waitcnt lgkmcnt(2)
	v_mfma_f32_32x32x16_bf16 v[2:17], v[224:227], v[74:77], v[2:17]
	v_exp_f32_e32 v48, v48
	v_exp_f32_e32 v49, v49
	v_add_f32_e32 v247, v46, v247
	v_add_f32_e32 v247, v47, v247
	v_cvt_pk_bf16_f32 v80, v46, v47
	v_cvt_pk_bf16_f32 v81, v48, v49
	v_add_f32_e32 v247, v48, v247
	v_add_f32_e32 v247, v49, v247
	s_waitcnt lgkmcnt(1)
	v_mfma_f32_32x32x16_bf16 v[18:33], v[212:215], v[78:81], v[18:33]
	s_waitcnt lgkmcnt(0)
	v_mfma_f32_32x32x16_bf16 v[2:17], v[242:245], v[78:81], v[2:17]
	v_add_f32_e32 v210, v210, v246
	v_add_f32_e32 v210, v210, v247
	s_cmp_ge_u32 s24, s16
	s_cbranch_scc1 .Lattn_fx_skipw1
	s_waitcnt vmcnt(3)
	ds_write_b128 v192, v[146:149] offset:18432
	s_waitcnt vmcnt(2)
	ds_write_b128 v204, v[150:153] offset:27648

; template <int HD, int MODE> ...
;     ...
;     int t = t0;
;     for (; t + 1 < t1; t += 2) { ATT_STEP(sa0, sa1, sb0, sb1, t, kstB, vstB, kstA, vstA); ATT_STEP(sb0, sb1, sa0, sa1, t + 1, kstA, vstA, kstB, vstB); }
;     if (t < t1) ATT_STEP(sa0, sa1, sb0, sb1, t, kstB, vstB, kstA, vstA);
.Lattn_fx_exit0:
	s_setprio 0
	s_movk_i32 s2, 0x4800
	s_branch .LBB0_508
.Lattn_fx_exit1:
	s_setprio 0
	s_mov_b32 s2, 0x9000
	s_branch .LBB0_508
